# up-projection epilogue keeps 16 gate loads in flight per wave (4 row-groups) instead of 12
# speedup vs baseline: 1.0107x; 1.0107x over previous
; DI float bflo(unsigned w) { return __uint_as_float(w << 16); }
; DI float bfhi(unsigned w) { return __uint_as_float(w & 0xffff0000u); }
;     DI void operator()(Acc& acc, const Unit& u, int wr, int wc, int fr, int fq) const {
;     ...
;         bf16_t* base = proj + (size_t)(u.pm * 256 + wr * 64 + fr) * NPJ + C_GL + u.pn * 256 + wc * 32 + fq * 8;
;         {
;             u32x4 g[2][4][2];
; #pragma unroll
;             for (int ai = 0; ai < 2; ++ai)
; #pragma unroll
;                 for (int m = 0; m < 4; ++m)
; #pragma unroll
;                     for (int bj = 0; bj < 2; ++bj) g[ai][m][bj] = *(const u32x4*)(base + (size_t)(ai * 128 + m * 16) * NPJ + u.k * 1024 + bj * 128);
; #pragma unroll
;             for (int ai = 0; ai < 2; ++ai)
; #pragma unroll
;                 for (int m = 0; m < 4; ++m)
; #pragma unroll
;                     for (int bj = 0; bj < 2; ++bj) { const u32x4 q = g[ai][m][bj]; f32x4& v0 = acc[ai][bj][m][0]; f32x4& v1 = acc[ai][bj][m][1];
;                         v0[0] *= bflo(q.x); v0[1] *= bfhi(q.x); v0[2] *= bflo(q.y); v0[3] *= bfhi(q.y); v1[0] *= bflo(q.z); v1[1] *= bfhi(q.z); v1[2] *= bflo(q.w); v1[3] *= bfhi(q.w); }
.LBB0_948:
	v_mov_b32_e32 v130, v1
	v_mov_b32_e32 v132, v172
	s_lshl_b32 s8, s30, 1
	v_add_u32_e32 v133, s39, v130
	v_mov_b64_e32 v[130:131], s[48:49]
	v_mad_i64_i32 v[130:131], s[24:25], v133, s41, v[130:131]
	v_lshl_add_u64 v[130:131], v[130:131], 0, s[8:9]
	s_mov_b32 s17, s9
	v_lshlrev_b32_e32 v132, 3, v132
	v_lshl_add_u64 v[130:131], v[130:131], 0, s[16:17]
	v_ashrrev_i32_e32 v133, 31, v132
	v_lshl_add_u64 v[130:131], v[132:133], 1, v[130:131]
	v_lshl_add_u64 v[166:167], v[130:131], 0, s[18:19]
	s_lshl_b32 s8, s84, 10
	v_lshl_add_u64 v[130:131], s[8:9], 1, v[166:167]
	s_nop 0
	v_readfirstlane_b32 s98, v130
	v_readfirstlane_b32 s99, v131
	v_bfe_u32 v146, v183, 5, 3
	v_mul_u32_u24_e32 v146, 0x3200, v146
	v_and_b32_e32 v147, 31, v183
	v_lshl_add_u32 v146, v147, 4, v146
	v_bfe_u32 v147, v183, 6, 2
	v_lshlrev_b32_e32 v147, 6, v147
	v_sub_u32_e32 v243, v146, v147
	s_cmp_eq_u32 s84, 2
	s_cbranch_scc1 .Lup3_final
	s_add_u32 s100, s98, 0x0
	s_addc_u32 s101, s99, 0
	global_load_dwordx4 v[184:187], v243, s[100:101]
	s_add_u32 s100, s98, 0x19000
	s_addc_u32 s101, s99, 0
	global_load_dwordx4 v[188:191], v243, s[100:101]
	s_add_u32 s100, s98, 0x0
	s_addc_u32 s101, s99, 0
	global_load_dwordx4 v[192:195], v243, s[100:101] offset:2048
	s_add_u32 s100, s98, 0x19000
	s_addc_u32 s101, s99, 0
	global_load_dwordx4 v[196:199], v243, s[100:101] offset:2048
	s_add_u32 s100, s98, 0x32000
	s_addc_u32 s101, s99, 0
	global_load_dwordx4 v[200:203], v243, s[100:101]
	s_add_u32 s100, s98, 0x4b000
	s_addc_u32 s101, s99, 0
	global_load_dwordx4 v[204:207], v243, s[100:101]
	s_add_u32 s100, s98, 0x32000
	s_addc_u32 s101, s99, 0
	global_load_dwordx4 v[208:211], v243, s[100:101] offset:2048
	s_add_u32 s100, s98, 0x4b000
	s_addc_u32 s101, s99, 0
	global_load_dwordx4 v[212:215], v243, s[100:101] offset:2048
	s_add_u32 s100, s98, 0x64000
	s_addc_u32 s101, s99, 0
	global_load_dwordx4 v[216:219], v243, s[100:101]
	s_add_u32 s100, s98, 0x7d000
	s_addc_u32 s101, s99, 0
	global_load_dwordx4 v[220:223], v243, s[100:101]
	s_add_u32 s100, s98, 0x64000
	s_addc_u32 s101, s99, 0
	global_load_dwordx4 v[224:227], v243, s[100:101] offset:2048
	s_add_u32 s100, s98, 0x7d000
	s_addc_u32 s101, s99, 0
	global_load_dwordx4 v[228:231], v243, s[100:101] offset:2048
	s_add_u32 s100, s98, 0x96000
	s_addc_u32 s101, s99, 0
	global_load_dwordx4 v[232:235], v243, s[100:101]
	s_add_u32 s100, s98, 0xaf000
	s_addc_u32 s101, s99, 0
	global_load_dwordx4 v[236:239], v243, s[100:101]
	s_add_u32 s100, s98, 0x96000
	s_addc_u32 s101, s99, 0
	global_load_dwordx4 v[132:135], v243, s[100:101] offset:2048
	s_add_u32 s100, s98, 0xaf000
	s_addc_u32 s101, s99, 0
	global_load_dwordx4 v[136:139], v243, s[100:101] offset:2048
	s_waitcnt vmcnt(12)
	v_lshlrev_b32_e32 v146, 16, v184
	v_and_b32_e32 v147, 0xffff0000, v184
	v_lshlrev_b32_e32 v148, 16, v192
	v_and_b32_e32 v149, 0xffff0000, v192
	v_lshlrev_b32_e32 v150, 16, v185
	v_and_b32_e32 v151, 0xffff0000, v185
	v_lshlrev_b32_e32 v152, 16, v193
	v_and_b32_e32 v153, 0xffff0000, v193
	v_rcp_f32_e32 v146, v146
	v_rcp_f32_e32 v147, v147
	v_rcp_f32_e32 v150, v150
	v_rcp_f32_e32 v151, v151
	s_nop 0
	v_pk_mul_f32 v[146:147], v[146:147], v[148:149]
	v_pk_mul_f32 v[150:151], v[150:151], v[152:153]
	v_pk_mul_f32 v[126:127], v[126:127], v[146:147]
	v_pk_mul_f32 v[128:129], v[128:129], v[150:151]
	v_lshlrev_b32_e32 v168, 16, v186
	v_and_b32_e32 v169, 0xffff0000, v186
	v_lshlrev_b32_e32 v178, 16, v194
	v_and_b32_e32 v179, 0xffff0000, v194
	v_lshlrev_b32_e32 v180, 16, v187
	v_and_b32_e32 v181, 0xffff0000, v187
	v_lshlrev_b32_e32 v244, 16, v195
	v_and_b32_e32 v245, 0xffff0000, v195
	v_rcp_f32_e32 v168, v168
	v_rcp_f32_e32 v169, v169
	v_rcp_f32_e32 v180, v180
	v_rcp_f32_e32 v181, v181
	s_nop 0
	v_pk_mul_f32 v[168:169], v[168:169], v[178:179]
	v_pk_mul_f32 v[180:181], v[180:181], v[244:245]
	v_pk_mul_f32 v[122:123], v[122:123], v[168:169]
	v_pk_mul_f32 v[124:125], v[124:125], v[180:181]
	v_lshlrev_b32_e32 v168, 16, v188
	v_and_b32_e32 v169, 0xffff0000, v188
	v_lshlrev_b32_e32 v178, 16, v196
	v_and_b32_e32 v179, 0xffff0000, v196
	v_lshlrev_b32_e32 v180, 16, v189
	v_and_b32_e32 v181, 0xffff0000, v189
	v_lshlrev_b32_e32 v244, 16, v197
	v_and_b32_e32 v245, 0xffff0000, v197
	v_rcp_f32_e32 v168, v168
	v_rcp_f32_e32 v169, v169
	v_rcp_f32_e32 v180, v180
	v_rcp_f32_e32 v181, v181
	s_nop 0
	v_pk_mul_f32 v[168:169], v[168:169], v[178:179]
	v_pk_mul_f32 v[180:181], v[180:181], v[244:245]
	v_pk_mul_f32 v[114:115], v[114:115], v[168:169]
	v_pk_mul_f32 v[116:117], v[116:117], v[180:181]
	v_lshlrev_b32_e32 v146, 16, v190
	v_and_b32_e32 v147, 0xffff0000, v190
	v_lshlrev_b32_e32 v148, 16, v198
	v_and_b32_e32 v149, 0xffff0000, v198
	v_lshlrev_b32_e32 v150, 16, v191
	v_and_b32_e32 v151, 0xffff0000, v191
	v_lshlrev_b32_e32 v152, 16, v199
	v_and_b32_e32 v153, 0xffff0000, v199
	v_rcp_f32_e32 v146, v146
	v_rcp_f32_e32 v147, v147
	v_rcp_f32_e32 v150, v150
	v_rcp_f32_e32 v151, v151
	s_nop 0
	v_pk_mul_f32 v[146:147], v[146:147], v[148:149]
	v_pk_mul_f32 v[150:151], v[150:151], v[152:153]
	v_pk_mul_f32 v[110:111], v[110:111], v[146:147]
	v_pk_mul_f32 v[112:113], v[112:113], v[150:151]
	s_add_u32 s100, s98, 0x190000
	s_addc_u32 s101, s99, 0
	global_load_dwordx4 v[184:187], v243, s[100:101]
	s_add_u32 s100, s98, 0x1a9000
	s_addc_u32 s101, s99, 0
	global_load_dwordx4 v[188:191], v243, s[100:101]
	s_add_u32 s100, s98, 0x190000
	s_addc_u32 s101, s99, 0
	global_load_dwordx4 v[192:195], v243, s[100:101] offset:2048
	s_add_u32 s100, s98, 0x1a9000
	s_addc_u32 s101, s99, 0
	global_load_dwordx4 v[196:199], v243, s[100:101] offset:2048
	s_waitcnt vmcnt(12)
; DI float bflo(unsigned w) { return __uint_as_float(w << 16); }
; DI float bfhi(unsigned w) { return __uint_as_float(w & 0xffff0000u); }
;     DI void operator()(Acc& acc, const Unit& u, int wr, int wc, int fr, int fq) const {
;     ...
;                     for (int bj = 0; bj < 2; ++bj) g[ai][m][bj] = *(const u32x4*)(base + (size_t)(ai * 128 + m * 16) * NPJ + u.k * 1024 + bj * 128);
; #pragma unroll
;             for (int ai = 0; ai < 2; ++ai)
; #pragma unroll
;                 for (int m = 0; m < 4; ++m)
; #pragma unroll
;                     for (int bj = 0; bj < 2; ++bj) { const u32x4 q = g[ai][m][bj]; f32x4& v0 = acc[ai][bj][m][0]; f32x4& v1 = acc[ai][bj][m][1];
;                         v0[0] *= bflo(q.x); v0[1] *= bfhi(q.x); v0[2] *= bflo(q.y); v0[3] *= bfhi(q.y); v1[0] *= bflo(q.z); v1[1] *= bfhi(q.z); v1[2] *= bflo(q.w); v1[3] *= bfhi(q.w); }
	v_lshlrev_b32_e32 v146, 16, v200
	v_and_b32_e32 v147, 0xffff0000, v200
	v_lshlrev_b32_e32 v148, 16, v208
	v_and_b32_e32 v149, 0xffff0000, v208
	v_lshlrev_b32_e32 v150, 16, v201
	v_and_b32_e32 v151, 0xffff0000, v201
	v_lshlrev_b32_e32 v152, 16, v209
	v_and_b32_e32 v153, 0xffff0000, v209
	v_rcp_f32_e32 v146, v146
	v_rcp_f32_e32 v147, v147
	v_rcp_f32_e32 v150, v150
	v_rcp_f32_e32 v151, v151
	s_nop 0
	v_pk_mul_f32 v[146:147], v[146:147], v[148:149]
	v_pk_mul_f32 v[150:151], v[150:151], v[152:153]
	v_pk_mul_f32 v[118:119], v[118:119], v[146:147]
	v_pk_mul_f32 v[120:121], v[120:121], v[150:151]
	v_lshlrev_b32_e32 v168, 16, v202
	v_and_b32_e32 v169, 0xffff0000, v202
	v_lshlrev_b32_e32 v178, 16, v210
	v_and_b32_e32 v179, 0xffff0000, v210
	v_lshlrev_b32_e32 v180, 16, v203
	v_and_b32_e32 v181, 0xffff0000, v203
	v_lshlrev_b32_e32 v244, 16, v211
	v_and_b32_e32 v245, 0xffff0000, v211
	v_rcp_f32_e32 v168, v168
	v_rcp_f32_e32 v169, v169
	v_rcp_f32_e32 v180, v180
	v_rcp_f32_e32 v181, v181
	s_nop 0
	v_pk_mul_f32 v[168:169], v[168:169], v[178:179]
	v_pk_mul_f32 v[180:181], v[180:181], v[244:245]
	v_pk_mul_f32 v[106:107], v[106:107], v[168:169]
	v_pk_mul_f32 v[108:109], v[108:109], v[180:181]
	v_lshlrev_b32_e32 v168, 16, v204
	v_and_b32_e32 v169, 0xffff0000, v204
	v_lshlrev_b32_e32 v178, 16, v212
	v_and_b32_e32 v179, 0xffff0000, v212
	v_lshlrev_b32_e32 v180, 16, v205
	v_and_b32_e32 v181, 0xffff0000, v205
	v_lshlrev_b32_e32 v244, 16, v213
	v_and_b32_e32 v245, 0xffff0000, v213
	v_rcp_f32_e32 v168, v168
	v_rcp_f32_e32 v169, v169
	v_rcp_f32_e32 v180, v180
	v_rcp_f32_e32 v181, v181
	s_nop 0
	v_pk_mul_f32 v[168:169], v[168:169], v[178:179]
	v_pk_mul_f32 v[180:181], v[180:181], v[244:245]
	v_pk_mul_f32 v[98:99], v[98:99], v[168:169]
	v_pk_mul_f32 v[100:101], v[100:101], v[180:181]
	v_lshlrev_b32_e32 v146, 16, v206
	v_and_b32_e32 v147, 0xffff0000, v206
	v_lshlrev_b32_e32 v148, 16, v214
	v_and_b32_e32 v149, 0xffff0000, v214
	v_lshlrev_b32_e32 v150, 16, v207
	v_and_b32_e32 v151, 0xffff0000, v207
	v_lshlrev_b32_e32 v152, 16, v215
	v_and_b32_e32 v153, 0xffff0000, v215
	v_rcp_f32_e32 v146, v146
	v_rcp_f32_e32 v147, v147
	v_rcp_f32_e32 v150, v150
	v_rcp_f32_e32 v151, v151
	s_nop 0
	v_pk_mul_f32 v[146:147], v[146:147], v[148:149]
	v_pk_mul_f32 v[150:151], v[150:151], v[152:153]
	v_pk_mul_f32 v[90:91], v[90:91], v[146:147]
	v_pk_mul_f32 v[92:93], v[92:93], v[150:151]
	s_add_u32 s100, s98, 0x1c2000
	s_addc_u32 s101, s99, 0
	global_load_dwordx4 v[200:203], v243, s[100:101]
	s_add_u32 s100, s98, 0x1db000
	s_addc_u32 s101, s99, 0
	global_load_dwordx4 v[204:207], v243, s[100:101]
	s_add_u32 s100, s98, 0x1c2000
	s_addc_u32 s101, s99, 0
	global_load_dwordx4 v[208:211], v243, s[100:101] offset:2048
	s_add_u32 s100, s98, 0x1db000
	s_addc_u32 s101, s99, 0
	global_load_dwordx4 v[212:215], v243, s[100:101] offset:2048
	s_waitcnt vmcnt(12)
	v_lshlrev_b32_e32 v146, 16, v216
	v_and_b32_e32 v147, 0xffff0000, v216
	v_lshlrev_b32_e32 v148, 16, v224
	v_and_b32_e32 v149, 0xffff0000, v224
	v_lshlrev_b32_e32 v150, 16, v217
	v_and_b32_e32 v151, 0xffff0000, v217
	v_lshlrev_b32_e32 v152, 16, v225
	v_and_b32_e32 v153, 0xffff0000, v225
	v_rcp_f32_e32 v146, v146
	v_rcp_f32_e32 v147, v147
	v_rcp_f32_e32 v150, v150
	v_rcp_f32_e32 v151, v151
	s_nop 0
	v_pk_mul_f32 v[146:147], v[146:147], v[148:149]
	v_pk_mul_f32 v[150:151], v[150:151], v[152:153]
	v_pk_mul_f32 v[102:103], v[102:103], v[146:147]
	v_pk_mul_f32 v[104:105], v[104:105], v[150:151]
	v_lshlrev_b32_e32 v168, 16, v218
	v_and_b32_e32 v169, 0xffff0000, v218
	v_lshlrev_b32_e32 v178, 16, v226
	v_and_b32_e32 v179, 0xffff0000, v226
	v_lshlrev_b32_e32 v180, 16, v219
	v_and_b32_e32 v181, 0xffff0000, v219
	v_lshlrev_b32_e32 v244, 16, v227
	v_and_b32_e32 v245, 0xffff0000, v227
	v_rcp_f32_e32 v168, v168
	v_rcp_f32_e32 v169, v169
	v_rcp_f32_e32 v180, v180
	v_rcp_f32_e32 v181, v181
	s_nop 0
	v_pk_mul_f32 v[168:169], v[168:169], v[178:179]
	v_pk_mul_f32 v[180:181], v[180:181], v[244:245]
	v_pk_mul_f32 v[94:95], v[94:95], v[168:169]
	v_pk_mul_f32 v[96:97], v[96:97], v[180:181]
	v_lshlrev_b32_e32 v168, 16, v220
	v_and_b32_e32 v169, 0xffff0000, v220
	v_lshlrev_b32_e32 v178, 16, v228
	v_and_b32_e32 v179, 0xffff0000, v228
	v_lshlrev_b32_e32 v180, 16, v221
	v_and_b32_e32 v181, 0xffff0000, v221
	v_lshlrev_b32_e32 v244, 16, v229
	v_and_b32_e32 v245, 0xffff0000, v229
	v_rcp_f32_e32 v168, v168
	v_rcp_f32_e32 v169, v169
	v_rcp_f32_e32 v180, v180
	v_rcp_f32_e32 v181, v181
	s_nop 0
	v_pk_mul_f32 v[168:169], v[168:169], v[178:179]
	v_pk_mul_f32 v[180:181], v[180:181], v[244:245]
	v_pk_mul_f32 v[82:83], v[82:83], v[168:169]
	v_pk_mul_f32 v[84:85], v[84:85], v[180:181]
	v_lshlrev_b32_e32 v146, 16, v222
	v_and_b32_e32 v147, 0xffff0000, v222
	v_lshlrev_b32_e32 v148, 16, v230
	v_and_b32_e32 v149, 0xffff0000, v230
	v_lshlrev_b32_e32 v150, 16, v223
	v_and_b32_e32 v151, 0xffff0000, v223
	v_lshlrev_b32_e32 v152, 16, v231
	v_and_b32_e32 v153, 0xffff0000, v231
	v_rcp_f32_e32 v146, v146
	v_rcp_f32_e32 v147, v147
	v_rcp_f32_e32 v150, v150
	v_rcp_f32_e32 v151, v151
	s_nop 0
	v_pk_mul_f32 v[146:147], v[146:147], v[148:149]
	v_pk_mul_f32 v[150:151], v[150:151], v[152:153]
	v_pk_mul_f32 v[74:75], v[74:75], v[146:147]
	v_pk_mul_f32 v[76:77], v[76:77], v[150:151]
	s_add_u32 s100, s98, 0x1f4000
	s_addc_u32 s101, s99, 0
	global_load_dwordx4 v[216:219], v243, s[100:101]
	s_add_u32 s100, s98, 0x20d000
	s_addc_u32 s101, s99, 0
	global_load_dwordx4 v[220:223], v243, s[100:101]
	s_add_u32 s100, s98, 0x1f4000
	s_addc_u32 s101, s99, 0
	global_load_dwordx4 v[224:227], v243, s[100:101] offset:2048
	s_add_u32 s100, s98, 0x20d000
	s_addc_u32 s101, s99, 0
	global_load_dwordx4 v[228:231], v243, s[100:101] offset:2048
	s_waitcnt vmcnt(12)
; DI float bflo(unsigned w) { return __uint_as_float(w << 16); }
; DI float bfhi(unsigned w) { return __uint_as_float(w & 0xffff0000u); }
;     DI void operator()(Acc& acc, const Unit& u, int wr, int wc, int fr, int fq) const {
;     ...
;                     for (int bj = 0; bj < 2; ++bj) g[ai][m][bj] = *(const u32x4*)(base + (size_t)(ai * 128 + m * 16) * NPJ + u.k * 1024 + bj * 128);
; #pragma unroll
;             for (int ai = 0; ai < 2; ++ai)
; #pragma unroll
;                 for (int m = 0; m < 4; ++m)
; #pragma unroll
;                     for (int bj = 0; bj < 2; ++bj) { const u32x4 q = g[ai][m][bj]; f32x4& v0 = acc[ai][bj][m][0]; f32x4& v1 = acc[ai][bj][m][1];
;                         v0[0] *= bflo(q.x); v0[1] *= bfhi(q.x); v0[2] *= bflo(q.y); v0[3] *= bfhi(q.y); v1[0] *= bflo(q.z); v1[1] *= bfhi(q.z); v1[2] *= bflo(q.w); v1[3] *= bfhi(q.w); }
	v_lshlrev_b32_e32 v146, 16, v232
	v_and_b32_e32 v147, 0xffff0000, v232
	v_lshlrev_b32_e32 v148, 16, v132
	v_and_b32_e32 v149, 0xffff0000, v132
	v_lshlrev_b32_e32 v150, 16, v233
	v_and_b32_e32 v151, 0xffff0000, v233
	v_lshlrev_b32_e32 v152, 16, v133
	v_and_b32_e32 v153, 0xffff0000, v133
	v_rcp_f32_e32 v146, v146
	v_rcp_f32_e32 v147, v147
	v_rcp_f32_e32 v150, v150
	v_rcp_f32_e32 v151, v151
	s_nop 0
	v_pk_mul_f32 v[146:147], v[146:147], v[148:149]
	v_pk_mul_f32 v[150:151], v[150:151], v[152:153]
	v_pk_mul_f32 v[86:87], v[86:87], v[146:147]
	v_pk_mul_f32 v[88:89], v[88:89], v[150:151]
	v_lshlrev_b32_e32 v168, 16, v234
	v_and_b32_e32 v169, 0xffff0000, v234
	v_lshlrev_b32_e32 v178, 16, v134
	v_and_b32_e32 v179, 0xffff0000, v134
	v_lshlrev_b32_e32 v180, 16, v235
	v_and_b32_e32 v181, 0xffff0000, v235
	v_lshlrev_b32_e32 v244, 16, v135
	v_and_b32_e32 v245, 0xffff0000, v135
	v_rcp_f32_e32 v168, v168
	v_rcp_f32_e32 v169, v169
	v_rcp_f32_e32 v180, v180
	v_rcp_f32_e32 v181, v181
	s_nop 0
	v_pk_mul_f32 v[168:169], v[168:169], v[178:179]
	v_pk_mul_f32 v[180:181], v[180:181], v[244:245]
	v_pk_mul_f32 v[78:79], v[78:79], v[168:169]
	v_pk_mul_f32 v[80:81], v[80:81], v[180:181]
	v_lshlrev_b32_e32 v168, 16, v236
	v_and_b32_e32 v169, 0xffff0000, v236
	v_lshlrev_b32_e32 v178, 16, v136
	v_and_b32_e32 v179, 0xffff0000, v136
	v_lshlrev_b32_e32 v180, 16, v237
	v_and_b32_e32 v181, 0xffff0000, v237
	v_lshlrev_b32_e32 v244, 16, v137
	v_and_b32_e32 v245, 0xffff0000, v137
	v_rcp_f32_e32 v168, v168
	v_rcp_f32_e32 v169, v169
	v_rcp_f32_e32 v180, v180
	v_rcp_f32_e32 v181, v181
	s_nop 0
	v_pk_mul_f32 v[168:169], v[168:169], v[178:179]
	v_pk_mul_f32 v[180:181], v[180:181], v[244:245]
	v_pk_mul_f32 v[70:71], v[70:71], v[168:169]
	v_pk_mul_f32 v[72:73], v[72:73], v[180:181]
	v_lshlrev_b32_e32 v146, 16, v238
	v_and_b32_e32 v147, 0xffff0000, v238
	v_lshlrev_b32_e32 v148, 16, v138
	v_and_b32_e32 v149, 0xffff0000, v138
	v_lshlrev_b32_e32 v150, 16, v239
	v_and_b32_e32 v151, 0xffff0000, v239
	v_lshlrev_b32_e32 v152, 16, v139
	v_and_b32_e32 v153, 0xffff0000, v139
	v_rcp_f32_e32 v146, v146
	v_rcp_f32_e32 v147, v147
	v_rcp_f32_e32 v150, v150
	v_rcp_f32_e32 v151, v151
	s_nop 0
	v_pk_mul_f32 v[146:147], v[146:147], v[148:149]
	v_pk_mul_f32 v[150:151], v[150:151], v[152:153]
	v_pk_mul_f32 v[66:67], v[66:67], v[146:147]
	v_pk_mul_f32 v[68:69], v[68:69], v[150:151]
	s_add_u32 s100, s98, 0x226000
	s_addc_u32 s101, s99, 0
	global_load_dwordx4 v[232:235], v243, s[100:101]
	s_add_u32 s100, s98, 0x23f000
	s_addc_u32 s101, s99, 0
	global_load_dwordx4 v[236:239], v243, s[100:101]
	s_add_u32 s100, s98, 0x226000
	s_addc_u32 s101, s99, 0
	global_load_dwordx4 v[132:135], v243, s[100:101] offset:2048
	s_add_u32 s100, s98, 0x23f000
	s_addc_u32 s101, s99, 0
	global_load_dwordx4 v[136:139], v243, s[100:101] offset:2048
	s_waitcnt vmcnt(12)
	v_lshlrev_b32_e32 v146, 16, v184
	v_and_b32_e32 v147, 0xffff0000, v184
	v_lshlrev_b32_e32 v148, 16, v192
	v_and_b32_e32 v149, 0xffff0000, v192
	v_lshlrev_b32_e32 v150, 16, v185
	v_and_b32_e32 v151, 0xffff0000, v185
	v_lshlrev_b32_e32 v152, 16, v193
	v_and_b32_e32 v153, 0xffff0000, v193
	v_rcp_f32_e32 v146, v146
	v_rcp_f32_e32 v147, v147
	v_rcp_f32_e32 v150, v150
	v_rcp_f32_e32 v151, v151
	s_nop 0
	v_pk_mul_f32 v[146:147], v[146:147], v[148:149]
	v_pk_mul_f32 v[150:151], v[150:151], v[152:153]
	v_pk_mul_f32 v[62:63], v[62:63], v[146:147]
	v_pk_mul_f32 v[64:65], v[64:65], v[150:151]
	v_lshlrev_b32_e32 v168, 16, v186
	v_and_b32_e32 v169, 0xffff0000, v186
	v_lshlrev_b32_e32 v178, 16, v194
	v_and_b32_e32 v179, 0xffff0000, v194
	v_lshlrev_b32_e32 v180, 16, v187
	v_and_b32_e32 v181, 0xffff0000, v187
	v_lshlrev_b32_e32 v244, 16, v195
	v_and_b32_e32 v245, 0xffff0000, v195
	v_rcp_f32_e32 v168, v168
	v_rcp_f32_e32 v169, v169
	v_rcp_f32_e32 v180, v180
	v_rcp_f32_e32 v181, v181
	s_nop 0
	v_pk_mul_f32 v[168:169], v[168:169], v[178:179]
	v_pk_mul_f32 v[180:181], v[180:181], v[244:245]
	v_pk_mul_f32 v[58:59], v[58:59], v[168:169]
	v_pk_mul_f32 v[60:61], v[60:61], v[180:181]
	v_lshlrev_b32_e32 v168, 16, v188
	v_and_b32_e32 v169, 0xffff0000, v188
	v_lshlrev_b32_e32 v178, 16, v196
	v_and_b32_e32 v179, 0xffff0000, v196
	v_lshlrev_b32_e32 v180, 16, v189
	v_and_b32_e32 v181, 0xffff0000, v189
	v_lshlrev_b32_e32 v244, 16, v197
	v_and_b32_e32 v245, 0xffff0000, v197
	v_rcp_f32_e32 v168, v168
	v_rcp_f32_e32 v169, v169
	v_rcp_f32_e32 v180, v180
	v_rcp_f32_e32 v181, v181
	s_nop 0
	v_pk_mul_f32 v[168:169], v[168:169], v[178:179]
	v_pk_mul_f32 v[180:181], v[180:181], v[244:245]
	v_pk_mul_f32 v[50:51], v[50:51], v[168:169]
	v_pk_mul_f32 v[52:53], v[52:53], v[180:181]
	v_lshlrev_b32_e32 v146, 16, v190
	v_and_b32_e32 v147, 0xffff0000, v190
	v_lshlrev_b32_e32 v148, 16, v198
	v_and_b32_e32 v149, 0xffff0000, v198
	v_lshlrev_b32_e32 v150, 16, v191
	v_and_b32_e32 v151, 0xffff0000, v191
	v_lshlrev_b32_e32 v152, 16, v199
	v_and_b32_e32 v153, 0xffff0000, v199
	v_rcp_f32_e32 v146, v146
	v_rcp_f32_e32 v147, v147
	v_rcp_f32_e32 v150, v150
	v_rcp_f32_e32 v151, v151
	s_nop 0
	v_pk_mul_f32 v[146:147], v[146:147], v[148:149]
	v_pk_mul_f32 v[150:151], v[150:151], v[152:153]
	v_pk_mul_f32 v[42:43], v[42:43], v[146:147]
	v_pk_mul_f32 v[44:45], v[44:45], v[150:151]
	s_waitcnt vmcnt(8)
; DI float bflo(unsigned w) { return __uint_as_float(w << 16); }
; DI float bfhi(unsigned w) { return __uint_as_float(w & 0xffff0000u); }
;     DI void operator()(Acc& acc, const Unit& u, int wr, int wc, int fr, int fq) const {
;     ...
;                     for (int bj = 0; bj < 2; ++bj) g[ai][m][bj] = *(const u32x4*)(base + (size_t)(ai * 128 + m * 16) * NPJ + u.k * 1024 + bj * 128);
; #pragma unroll
;             for (int ai = 0; ai < 2; ++ai)
; #pragma unroll
;                 for (int m = 0; m < 4; ++m)
; #pragma unroll
;                     for (int bj = 0; bj < 2; ++bj) { const u32x4 q = g[ai][m][bj]; f32x4& v0 = acc[ai][bj][m][0]; f32x4& v1 = acc[ai][bj][m][1];
;                         v0[0] *= bflo(q.x); v0[1] *= bfhi(q.x); v0[2] *= bflo(q.y); v0[3] *= bfhi(q.y); v1[0] *= bflo(q.z); v1[1] *= bfhi(q.z); v1[2] *= bflo(q.w); v1[3] *= bfhi(q.w); }
	v_lshlrev_b32_e32 v146, 16, v200
	v_and_b32_e32 v147, 0xffff0000, v200
	v_lshlrev_b32_e32 v148, 16, v208
	v_and_b32_e32 v149, 0xffff0000, v208
	v_lshlrev_b32_e32 v150, 16, v201
	v_and_b32_e32 v151, 0xffff0000, v201
	v_lshlrev_b32_e32 v152, 16, v209
	v_and_b32_e32 v153, 0xffff0000, v209
	v_rcp_f32_e32 v146, v146
	v_rcp_f32_e32 v147, v147
	v_rcp_f32_e32 v150, v150
	v_rcp_f32_e32 v151, v151
	s_nop 0
	v_pk_mul_f32 v[146:147], v[146:147], v[148:149]
	v_pk_mul_f32 v[150:151], v[150:151], v[152:153]
	v_pk_mul_f32 v[54:55], v[54:55], v[146:147]
	v_pk_mul_f32 v[56:57], v[56:57], v[150:151]
	v_lshlrev_b32_e32 v168, 16, v202
	v_and_b32_e32 v169, 0xffff0000, v202
	v_lshlrev_b32_e32 v178, 16, v210
	v_and_b32_e32 v179, 0xffff0000, v210
	v_lshlrev_b32_e32 v180, 16, v203
	v_and_b32_e32 v181, 0xffff0000, v203
	v_lshlrev_b32_e32 v244, 16, v211
	v_and_b32_e32 v245, 0xffff0000, v211
	v_rcp_f32_e32 v168, v168
	v_rcp_f32_e32 v169, v169
	v_rcp_f32_e32 v180, v180
	v_rcp_f32_e32 v181, v181
	s_nop 0
	v_pk_mul_f32 v[168:169], v[168:169], v[178:179]
	v_pk_mul_f32 v[180:181], v[180:181], v[244:245]
	v_pk_mul_f32 v[46:47], v[46:47], v[168:169]
	v_pk_mul_f32 v[48:49], v[48:49], v[180:181]
	v_lshlrev_b32_e32 v168, 16, v204
	v_and_b32_e32 v169, 0xffff0000, v204
	v_lshlrev_b32_e32 v178, 16, v212
	v_and_b32_e32 v179, 0xffff0000, v212
	v_lshlrev_b32_e32 v180, 16, v205
	v_and_b32_e32 v181, 0xffff0000, v205
	v_lshlrev_b32_e32 v244, 16, v213
	v_and_b32_e32 v245, 0xffff0000, v213
	v_rcp_f32_e32 v168, v168
	v_rcp_f32_e32 v169, v169
	v_rcp_f32_e32 v180, v180
	v_rcp_f32_e32 v181, v181
	s_nop 0
	v_pk_mul_f32 v[168:169], v[168:169], v[178:179]
	v_pk_mul_f32 v[180:181], v[180:181], v[244:245]
	v_pk_mul_f32 v[34:35], v[34:35], v[168:169]
	v_pk_mul_f32 v[36:37], v[36:37], v[180:181]
	v_lshlrev_b32_e32 v146, 16, v206
	v_and_b32_e32 v147, 0xffff0000, v206
	v_lshlrev_b32_e32 v148, 16, v214
	v_and_b32_e32 v149, 0xffff0000, v214
	v_lshlrev_b32_e32 v150, 16, v207
	v_and_b32_e32 v151, 0xffff0000, v207
	v_lshlrev_b32_e32 v152, 16, v215
	v_and_b32_e32 v153, 0xffff0000, v215
	v_rcp_f32_e32 v146, v146
	v_rcp_f32_e32 v147, v147
	v_rcp_f32_e32 v150, v150
	v_rcp_f32_e32 v151, v151
	s_nop 0
	v_pk_mul_f32 v[146:147], v[146:147], v[148:149]
	v_pk_mul_f32 v[150:151], v[150:151], v[152:153]
	v_pk_mul_f32 v[26:27], v[26:27], v[146:147]
	v_pk_mul_f32 v[28:29], v[28:29], v[150:151]
	s_waitcnt vmcnt(4)
; DI float bflo(unsigned w) { return __uint_as_float(w << 16); }
; DI float bfhi(unsigned w) { return __uint_as_float(w & 0xffff0000u); }
;     DI void operator()(Acc& acc, const Unit& u, int wr, int wc, int fr, int fq) const {
;     ...
;                     for (int bj = 0; bj < 2; ++bj) g[ai][m][bj] = *(const u32x4*)(base + (size_t)(ai * 128 + m * 16) * NPJ + u.k * 1024 + bj * 128);
; #pragma unroll
;             for (int ai = 0; ai < 2; ++ai)
; #pragma unroll
;                 for (int m = 0; m < 4; ++m)
; #pragma unroll
;                     for (int bj = 0; bj < 2; ++bj) { const u32x4 q = g[ai][m][bj]; f32x4& v0 = acc[ai][bj][m][0]; f32x4& v1 = acc[ai][bj][m][1];
;                         v0[0] *= bflo(q.x); v0[1] *= bfhi(q.x); v0[2] *= bflo(q.y); v0[3] *= bfhi(q.y); v1[0] *= bflo(q.z); v1[1] *= bfhi(q.z); v1[2] *= bflo(q.w); v1[3] *= bfhi(q.w); }
	v_lshlrev_b32_e32 v146, 16, v216
	v_and_b32_e32 v147, 0xffff0000, v216
	v_lshlrev_b32_e32 v148, 16, v224
	v_and_b32_e32 v149, 0xffff0000, v224
	v_lshlrev_b32_e32 v150, 16, v217
	v_and_b32_e32 v151, 0xffff0000, v217
	v_lshlrev_b32_e32 v152, 16, v225
	v_and_b32_e32 v153, 0xffff0000, v225
	v_rcp_f32_e32 v146, v146
	v_rcp_f32_e32 v147, v147
	v_rcp_f32_e32 v150, v150
	v_rcp_f32_e32 v151, v151
	s_nop 0
	v_pk_mul_f32 v[146:147], v[146:147], v[148:149]
	v_pk_mul_f32 v[150:151], v[150:151], v[152:153]
	v_pk_mul_f32 v[38:39], v[38:39], v[146:147]
	v_pk_mul_f32 v[40:41], v[40:41], v[150:151]
	v_lshlrev_b32_e32 v168, 16, v218
	v_and_b32_e32 v169, 0xffff0000, v218
	v_lshlrev_b32_e32 v178, 16, v226
	v_and_b32_e32 v179, 0xffff0000, v226
	v_lshlrev_b32_e32 v180, 16, v219
	v_and_b32_e32 v181, 0xffff0000, v219
	v_lshlrev_b32_e32 v244, 16, v227
	v_and_b32_e32 v245, 0xffff0000, v227
	v_rcp_f32_e32 v168, v168
	v_rcp_f32_e32 v169, v169
	v_rcp_f32_e32 v180, v180
	v_rcp_f32_e32 v181, v181
	s_nop 0
	v_pk_mul_f32 v[168:169], v[168:169], v[178:179]
	v_pk_mul_f32 v[180:181], v[180:181], v[244:245]
	v_pk_mul_f32 v[30:31], v[30:31], v[168:169]
	v_pk_mul_f32 v[32:33], v[32:33], v[180:181]
	v_lshlrev_b32_e32 v168, 16, v220
	v_and_b32_e32 v169, 0xffff0000, v220
	v_lshlrev_b32_e32 v178, 16, v228
	v_and_b32_e32 v179, 0xffff0000, v228
	v_lshlrev_b32_e32 v180, 16, v221
	v_and_b32_e32 v181, 0xffff0000, v221
	v_lshlrev_b32_e32 v244, 16, v229
	v_and_b32_e32 v245, 0xffff0000, v229
	v_rcp_f32_e32 v168, v168
	v_rcp_f32_e32 v169, v169
	v_rcp_f32_e32 v180, v180
	v_rcp_f32_e32 v181, v181
	s_nop 0
	v_pk_mul_f32 v[168:169], v[168:169], v[178:179]
	v_pk_mul_f32 v[180:181], v[180:181], v[244:245]
	v_pk_mul_f32 v[18:19], v[18:19], v[168:169]
	v_pk_mul_f32 v[20:21], v[20:21], v[180:181]
	v_lshlrev_b32_e32 v146, 16, v222
	v_and_b32_e32 v147, 0xffff0000, v222
	v_lshlrev_b32_e32 v148, 16, v230
	v_and_b32_e32 v149, 0xffff0000, v230
	v_lshlrev_b32_e32 v150, 16, v223
	v_and_b32_e32 v151, 0xffff0000, v223
	v_lshlrev_b32_e32 v152, 16, v231
	v_and_b32_e32 v153, 0xffff0000, v231
	v_rcp_f32_e32 v146, v146
	v_rcp_f32_e32 v147, v147
	v_rcp_f32_e32 v150, v150
	v_rcp_f32_e32 v151, v151
	s_nop 0
	v_pk_mul_f32 v[146:147], v[146:147], v[148:149]
	v_pk_mul_f32 v[150:151], v[150:151], v[152:153]
	v_pk_mul_f32 v[10:11], v[10:11], v[146:147]
	v_pk_mul_f32 v[12:13], v[12:13], v[150:151]
	s_waitcnt vmcnt(0)
	v_lshlrev_b32_e32 v146, 16, v232
	v_and_b32_e32 v147, 0xffff0000, v232
	v_lshlrev_b32_e32 v148, 16, v132
	v_and_b32_e32 v149, 0xffff0000, v132
	v_lshlrev_b32_e32 v150, 16, v233
	v_and_b32_e32 v151, 0xffff0000, v233
	v_lshlrev_b32_e32 v152, 16, v133
	v_and_b32_e32 v153, 0xffff0000, v133
	v_rcp_f32_e32 v146, v146
	v_rcp_f32_e32 v147, v147
	v_rcp_f32_e32 v150, v150
	v_rcp_f32_e32 v151, v151
	s_nop 0
	v_pk_mul_f32 v[146:147], v[146:147], v[148:149]
	v_pk_mul_f32 v[150:151], v[150:151], v[152:153]
	v_pk_mul_f32 v[22:23], v[22:23], v[146:147]
	v_pk_mul_f32 v[24:25], v[24:25], v[150:151]
	v_lshlrev_b32_e32 v168, 16, v234
	v_and_b32_e32 v169, 0xffff0000, v234
	v_lshlrev_b32_e32 v178, 16, v134
	v_and_b32_e32 v179, 0xffff0000, v134
	v_lshlrev_b32_e32 v180, 16, v235
	v_and_b32_e32 v181, 0xffff0000, v235
	v_lshlrev_b32_e32 v244, 16, v135
	v_and_b32_e32 v245, 0xffff0000, v135
	v_rcp_f32_e32 v168, v168
	v_rcp_f32_e32 v169, v169
	v_rcp_f32_e32 v180, v180
	v_rcp_f32_e32 v181, v181
	s_nop 0
	v_pk_mul_f32 v[168:169], v[168:169], v[178:179]
	v_pk_mul_f32 v[180:181], v[180:181], v[244:245]
	v_pk_mul_f32 v[14:15], v[14:15], v[168:169]
	v_pk_mul_f32 v[16:17], v[16:17], v[180:181]
	v_lshlrev_b32_e32 v168, 16, v236
	v_and_b32_e32 v169, 0xffff0000, v236
	v_lshlrev_b32_e32 v178, 16, v136
	v_and_b32_e32 v179, 0xffff0000, v136
	v_lshlrev_b32_e32 v180, 16, v237
	v_and_b32_e32 v181, 0xffff0000, v237
	v_lshlrev_b32_e32 v244, 16, v137
	v_and_b32_e32 v245, 0xffff0000, v137
	v_rcp_f32_e32 v168, v168
	v_rcp_f32_e32 v169, v169
	v_rcp_f32_e32 v180, v180
	v_rcp_f32_e32 v181, v181
	s_nop 0
	v_pk_mul_f32 v[168:169], v[168:169], v[178:179]
	v_pk_mul_f32 v[180:181], v[180:181], v[244:245]
	v_pk_mul_f32 v[6:7], v[6:7], v[168:169]
	v_pk_mul_f32 v[8:9], v[8:9], v[180:181]
	v_lshlrev_b32_e32 v146, 16, v238
	v_and_b32_e32 v147, 0xffff0000, v238
	v_lshlrev_b32_e32 v148, 16, v138
	v_and_b32_e32 v149, 0xffff0000, v138
	v_lshlrev_b32_e32 v150, 16, v239
	v_and_b32_e32 v151, 0xffff0000, v239
	v_lshlrev_b32_e32 v152, 16, v139
	v_and_b32_e32 v153, 0xffff0000, v139
	v_rcp_f32_e32 v146, v146
	v_rcp_f32_e32 v147, v147
	v_rcp_f32_e32 v150, v150
	v_rcp_f32_e32 v151, v151
	s_nop 0
	v_pk_mul_f32 v[146:147], v[146:147], v[148:149]
	v_pk_mul_f32 v[150:151], v[150:151], v[152:153]
	v_pk_mul_f32 v[2:3], v[2:3], v[146:147]
	v_pk_mul_f32 v[4:5], v[4:5], v[150:151]
	s_branch .Lup3_tail

; DI float bflo(unsigned w) { return __uint_as_float(w << 16); }
; DI float bfhi(unsigned w) { return __uint_as_float(w & 0xffff0000u); }
;     DI void operator()(Acc& acc, const Unit& u, int wr, int wc, int fr, int fq) const {
;     ...
;         bf16_t* base = proj + (size_t)(u.pm * 256 + wr * 64 + fr) * NPJ + C_GL + u.pn * 256 + wc * 32 + fq * 8;
;         {
;             u32x4 g[2][4][2];
; #pragma unroll
;             for (int ai = 0; ai < 2; ++ai)
; #pragma unroll
;                 for (int m = 0; m < 4; ++m)
; #pragma unroll
;                     for (int bj = 0; bj < 2; ++bj) g[ai][m][bj] = *(const u32x4*)(base + (size_t)(ai * 128 + m * 16) * NPJ + u.k * 1024 + bj * 128);
; #pragma unroll
;             for (int ai = 0; ai < 2; ++ai)
; #pragma unroll
;                 for (int m = 0; m < 4; ++m)
; #pragma unroll
;                     for (int bj = 0; bj < 2; ++bj) { const u32x4 q = g[ai][m][bj]; f32x4& v0 = acc[ai][bj][m][0]; f32x4& v1 = acc[ai][bj][m][1];
;                         v0[0] *= bflo(q.x); v0[1] *= bfhi(q.x); v0[2] *= bflo(q.y); v0[3] *= bfhi(q.y); v1[0] *= bflo(q.z); v1[1] *= bfhi(q.z); v1[2] *= bflo(q.w); v1[3] *= bfhi(q.w); }
.LBB0_1266:
	v_mov_b32_e32 v130, v1
	v_mov_b32_e32 v132, v170
	s_lshl_b32 s22, s69, 8
	s_add_i32 s22, s22, s34
	v_add_u32_e32 v133, s22, v130
	v_mov_b64_e32 v[130:131], s[48:49]
	v_mad_i64_i32 v[130:131], s[22:23], v133, s40, v[130:131]
	s_lshl_b32 s22, s68, 8
	s_ashr_i32 s23, s22, 31
	v_lshl_add_u64 v[130:131], s[22:23], 1, v[130:131]
	v_lshlrev_b32_e32 v132, 3, v132
	v_lshl_add_u64 v[130:131], v[130:131], 0, s[8:9]
	v_ashrrev_i32_e32 v133, 31, v132
	v_lshl_add_u64 v[130:131], v[132:133], 1, v[130:131]
	s_lshl_b32 s22, s67, 10
	v_lshl_add_u64 v[166:167], v[130:131], 0, s[16:17]
	s_ashr_i32 s23, s22, 31
	v_lshl_add_u64 v[130:131], s[22:23], 1, v[166:167]
	s_nop 0
	v_readfirstlane_b32 s98, v130
	v_readfirstlane_b32 s99, v131
	v_bfe_u32 v148, v183, 5, 3
	v_mul_u32_u24_e32 v148, 0x3200, v148
	v_and_b32_e32 v149, 31, v183
	v_lshl_add_u32 v148, v149, 4, v148
	v_bfe_u32 v149, v183, 6, 2
	v_lshlrev_b32_e32 v149, 6, v149
	v_sub_u32_e32 v243, v148, v149
	s_cmp_eq_u32 s67, 2
	s_cbranch_scc1 .Lup6_final
	s_add_u32 s100, s98, 0x0
	s_addc_u32 s101, s99, 0
	global_load_dwordx4 v[184:187], v243, s[100:101]
	s_add_u32 s100, s98, 0x19000
	s_addc_u32 s101, s99, 0
	global_load_dwordx4 v[188:191], v243, s[100:101]
	s_add_u32 s100, s98, 0x0
	s_addc_u32 s101, s99, 0
	global_load_dwordx4 v[192:195], v243, s[100:101] offset:2048
	s_add_u32 s100, s98, 0x19000
	s_addc_u32 s101, s99, 0
	global_load_dwordx4 v[196:199], v243, s[100:101] offset:2048
	s_add_u32 s100, s98, 0x32000
	s_addc_u32 s101, s99, 0
	global_load_dwordx4 v[200:203], v243, s[100:101]
	s_add_u32 s100, s98, 0x4b000
	s_addc_u32 s101, s99, 0
	global_load_dwordx4 v[204:207], v243, s[100:101]
	s_add_u32 s100, s98, 0x32000
	s_addc_u32 s101, s99, 0
	global_load_dwordx4 v[208:211], v243, s[100:101] offset:2048
	s_add_u32 s100, s98, 0x4b000
	s_addc_u32 s101, s99, 0
	global_load_dwordx4 v[212:215], v243, s[100:101] offset:2048
	s_add_u32 s100, s98, 0x64000
	s_addc_u32 s101, s99, 0
	global_load_dwordx4 v[216:219], v243, s[100:101]
	s_add_u32 s100, s98, 0x7d000
	s_addc_u32 s101, s99, 0
	global_load_dwordx4 v[220:223], v243, s[100:101]
	s_add_u32 s100, s98, 0x64000
	s_addc_u32 s101, s99, 0
	global_load_dwordx4 v[224:227], v243, s[100:101] offset:2048
	s_add_u32 s100, s98, 0x7d000
	s_addc_u32 s101, s99, 0
	global_load_dwordx4 v[228:231], v243, s[100:101] offset:2048
	s_add_u32 s100, s98, 0x96000
	s_addc_u32 s101, s99, 0
	global_load_dwordx4 v[232:235], v243, s[100:101]
	s_add_u32 s100, s98, 0xaf000
	s_addc_u32 s101, s99, 0
	global_load_dwordx4 v[236:239], v243, s[100:101]
	s_add_u32 s100, s98, 0x96000
	s_addc_u32 s101, s99, 0
	global_load_dwordx4 v[132:135], v243, s[100:101] offset:2048
	s_add_u32 s100, s98, 0xaf000
	s_addc_u32 s101, s99, 0
	global_load_dwordx4 v[136:139], v243, s[100:101] offset:2048
	s_waitcnt vmcnt(12)
	v_lshlrev_b32_e32 v148, 16, v184
	v_and_b32_e32 v149, 0xffff0000, v184
	v_lshlrev_b32_e32 v150, 16, v192
	v_and_b32_e32 v151, 0xffff0000, v192
	v_lshlrev_b32_e32 v152, 16, v185
	v_and_b32_e32 v153, 0xffff0000, v185
	v_lshlrev_b32_e32 v168, 16, v193
	v_and_b32_e32 v169, 0xffff0000, v193
	v_rcp_f32_e32 v148, v148
	v_rcp_f32_e32 v149, v149
	v_rcp_f32_e32 v152, v152
	v_rcp_f32_e32 v153, v153
	s_nop 0
	v_pk_mul_f32 v[148:149], v[148:149], v[150:151]
	v_pk_mul_f32 v[152:153], v[152:153], v[168:169]
	v_pk_mul_f32 v[126:127], v[126:127], v[148:149]
	v_pk_mul_f32 v[128:129], v[128:129], v[152:153]
	v_lshlrev_b32_e32 v176, 16, v186
	v_and_b32_e32 v177, 0xffff0000, v186
	v_lshlrev_b32_e32 v178, 16, v194
	v_and_b32_e32 v179, 0xffff0000, v194
	v_lshlrev_b32_e32 v180, 16, v187
	v_and_b32_e32 v181, 0xffff0000, v187
	v_lshlrev_b32_e32 v244, 16, v195
	v_and_b32_e32 v245, 0xffff0000, v195
	v_rcp_f32_e32 v176, v176
	v_rcp_f32_e32 v177, v177
	v_rcp_f32_e32 v180, v180
	v_rcp_f32_e32 v181, v181
	s_nop 0
	v_pk_mul_f32 v[176:177], v[176:177], v[178:179]
	v_pk_mul_f32 v[180:181], v[180:181], v[244:245]
	v_pk_mul_f32 v[122:123], v[122:123], v[176:177]
	v_pk_mul_f32 v[124:125], v[124:125], v[180:181]
	v_lshlrev_b32_e32 v176, 16, v188
	v_and_b32_e32 v177, 0xffff0000, v188
	v_lshlrev_b32_e32 v178, 16, v196
	v_and_b32_e32 v179, 0xffff0000, v196
	v_lshlrev_b32_e32 v180, 16, v189
	v_and_b32_e32 v181, 0xffff0000, v189
	v_lshlrev_b32_e32 v244, 16, v197
	v_and_b32_e32 v245, 0xffff0000, v197
	v_rcp_f32_e32 v176, v176
	v_rcp_f32_e32 v177, v177
	v_rcp_f32_e32 v180, v180
	v_rcp_f32_e32 v181, v181
	s_nop 0
	v_pk_mul_f32 v[176:177], v[176:177], v[178:179]
	v_pk_mul_f32 v[180:181], v[180:181], v[244:245]
	v_pk_mul_f32 v[114:115], v[114:115], v[176:177]
	v_pk_mul_f32 v[116:117], v[116:117], v[180:181]
	v_lshlrev_b32_e32 v148, 16, v190
	v_and_b32_e32 v149, 0xffff0000, v190
	v_lshlrev_b32_e32 v150, 16, v198
	v_and_b32_e32 v151, 0xffff0000, v198
	v_lshlrev_b32_e32 v152, 16, v191
	v_and_b32_e32 v153, 0xffff0000, v191
	v_lshlrev_b32_e32 v168, 16, v199
	v_and_b32_e32 v169, 0xffff0000, v199
	v_rcp_f32_e32 v148, v148
	v_rcp_f32_e32 v149, v149
	v_rcp_f32_e32 v152, v152
	v_rcp_f32_e32 v153, v153
	s_nop 0
	v_pk_mul_f32 v[148:149], v[148:149], v[150:151]
	v_pk_mul_f32 v[152:153], v[152:153], v[168:169]
	v_pk_mul_f32 v[110:111], v[110:111], v[148:149]
	v_pk_mul_f32 v[112:113], v[112:113], v[152:153]
	s_add_u32 s100, s98, 0x190000
	s_addc_u32 s101, s99, 0
	global_load_dwordx4 v[184:187], v243, s[100:101]
	s_add_u32 s100, s98, 0x1a9000
	s_addc_u32 s101, s99, 0
	global_load_dwordx4 v[188:191], v243, s[100:101]
	s_add_u32 s100, s98, 0x190000
	s_addc_u32 s101, s99, 0
	global_load_dwordx4 v[192:195], v243, s[100:101] offset:2048
	s_add_u32 s100, s98, 0x1a9000
	s_addc_u32 s101, s99, 0
	global_load_dwordx4 v[196:199], v243, s[100:101] offset:2048
	s_waitcnt vmcnt(12)
; DI float bflo(unsigned w) { return __uint_as_float(w << 16); }
; DI float bfhi(unsigned w) { return __uint_as_float(w & 0xffff0000u); }
;     DI void operator()(Acc& acc, const Unit& u, int wr, int wc, int fr, int fq) const {
;     ...
;                     for (int bj = 0; bj < 2; ++bj) g[ai][m][bj] = *(const u32x4*)(base + (size_t)(ai * 128 + m * 16) * NPJ + u.k * 1024 + bj * 128);
; #pragma unroll
;             for (int ai = 0; ai < 2; ++ai)
; #pragma unroll
;                 for (int m = 0; m < 4; ++m)
; #pragma unroll
;                     for (int bj = 0; bj < 2; ++bj) { const u32x4 q = g[ai][m][bj]; f32x4& v0 = acc[ai][bj][m][0]; f32x4& v1 = acc[ai][bj][m][1];
;                         v0[0] *= bflo(q.x); v0[1] *= bfhi(q.x); v0[2] *= bflo(q.y); v0[3] *= bfhi(q.y); v1[0] *= bflo(q.z); v1[1] *= bfhi(q.z); v1[2] *= bflo(q.w); v1[3] *= bfhi(q.w); }
	v_lshlrev_b32_e32 v148, 16, v200
	v_and_b32_e32 v149, 0xffff0000, v200
	v_lshlrev_b32_e32 v150, 16, v208
	v_and_b32_e32 v151, 0xffff0000, v208
	v_lshlrev_b32_e32 v152, 16, v201
	v_and_b32_e32 v153, 0xffff0000, v201
	v_lshlrev_b32_e32 v168, 16, v209
	v_and_b32_e32 v169, 0xffff0000, v209
	v_rcp_f32_e32 v148, v148
	v_rcp_f32_e32 v149, v149
	v_rcp_f32_e32 v152, v152
	v_rcp_f32_e32 v153, v153
	s_nop 0
	v_pk_mul_f32 v[148:149], v[148:149], v[150:151]
	v_pk_mul_f32 v[152:153], v[152:153], v[168:169]
	v_pk_mul_f32 v[118:119], v[118:119], v[148:149]
	v_pk_mul_f32 v[120:121], v[120:121], v[152:153]
	v_lshlrev_b32_e32 v176, 16, v202
	v_and_b32_e32 v177, 0xffff0000, v202
	v_lshlrev_b32_e32 v178, 16, v210
	v_and_b32_e32 v179, 0xffff0000, v210
	v_lshlrev_b32_e32 v180, 16, v203
	v_and_b32_e32 v181, 0xffff0000, v203
	v_lshlrev_b32_e32 v244, 16, v211
	v_and_b32_e32 v245, 0xffff0000, v211
	v_rcp_f32_e32 v176, v176
	v_rcp_f32_e32 v177, v177
	v_rcp_f32_e32 v180, v180
	v_rcp_f32_e32 v181, v181
	s_nop 0
	v_pk_mul_f32 v[176:177], v[176:177], v[178:179]
	v_pk_mul_f32 v[180:181], v[180:181], v[244:245]
	v_pk_mul_f32 v[106:107], v[106:107], v[176:177]
	v_pk_mul_f32 v[108:109], v[108:109], v[180:181]
	v_lshlrev_b32_e32 v176, 16, v204
	v_and_b32_e32 v177, 0xffff0000, v204
	v_lshlrev_b32_e32 v178, 16, v212
	v_and_b32_e32 v179, 0xffff0000, v212
	v_lshlrev_b32_e32 v180, 16, v205
	v_and_b32_e32 v181, 0xffff0000, v205
	v_lshlrev_b32_e32 v244, 16, v213
	v_and_b32_e32 v245, 0xffff0000, v213
	v_rcp_f32_e32 v176, v176
	v_rcp_f32_e32 v177, v177
	v_rcp_f32_e32 v180, v180
	v_rcp_f32_e32 v181, v181
	s_nop 0
	v_pk_mul_f32 v[176:177], v[176:177], v[178:179]
	v_pk_mul_f32 v[180:181], v[180:181], v[244:245]
	v_pk_mul_f32 v[98:99], v[98:99], v[176:177]
	v_pk_mul_f32 v[100:101], v[100:101], v[180:181]
	v_lshlrev_b32_e32 v148, 16, v206
	v_and_b32_e32 v149, 0xffff0000, v206
	v_lshlrev_b32_e32 v150, 16, v214
	v_and_b32_e32 v151, 0xffff0000, v214
	v_lshlrev_b32_e32 v152, 16, v207
	v_and_b32_e32 v153, 0xffff0000, v207
	v_lshlrev_b32_e32 v168, 16, v215
	v_and_b32_e32 v169, 0xffff0000, v215
	v_rcp_f32_e32 v148, v148
	v_rcp_f32_e32 v149, v149
	v_rcp_f32_e32 v152, v152
	v_rcp_f32_e32 v153, v153
	s_nop 0
	v_pk_mul_f32 v[148:149], v[148:149], v[150:151]
	v_pk_mul_f32 v[152:153], v[152:153], v[168:169]
	v_pk_mul_f32 v[90:91], v[90:91], v[148:149]
	v_pk_mul_f32 v[92:93], v[92:93], v[152:153]
	s_add_u32 s100, s98, 0x1c2000
	s_addc_u32 s101, s99, 0
	global_load_dwordx4 v[200:203], v243, s[100:101]
	s_add_u32 s100, s98, 0x1db000
	s_addc_u32 s101, s99, 0
	global_load_dwordx4 v[204:207], v243, s[100:101]
	s_add_u32 s100, s98, 0x1c2000
	s_addc_u32 s101, s99, 0
	global_load_dwordx4 v[208:211], v243, s[100:101] offset:2048
	s_add_u32 s100, s98, 0x1db000
	s_addc_u32 s101, s99, 0
	global_load_dwordx4 v[212:215], v243, s[100:101] offset:2048
	s_waitcnt vmcnt(12)
	v_lshlrev_b32_e32 v148, 16, v216
	v_and_b32_e32 v149, 0xffff0000, v216
	v_lshlrev_b32_e32 v150, 16, v224
	v_and_b32_e32 v151, 0xffff0000, v224
	v_lshlrev_b32_e32 v152, 16, v217
	v_and_b32_e32 v153, 0xffff0000, v217
	v_lshlrev_b32_e32 v168, 16, v225
	v_and_b32_e32 v169, 0xffff0000, v225
	v_rcp_f32_e32 v148, v148
	v_rcp_f32_e32 v149, v149
	v_rcp_f32_e32 v152, v152
	v_rcp_f32_e32 v153, v153
	s_nop 0
	v_pk_mul_f32 v[148:149], v[148:149], v[150:151]
	v_pk_mul_f32 v[152:153], v[152:153], v[168:169]
	v_pk_mul_f32 v[102:103], v[102:103], v[148:149]
	v_pk_mul_f32 v[104:105], v[104:105], v[152:153]
	v_lshlrev_b32_e32 v176, 16, v218
	v_and_b32_e32 v177, 0xffff0000, v218
	v_lshlrev_b32_e32 v178, 16, v226
	v_and_b32_e32 v179, 0xffff0000, v226
	v_lshlrev_b32_e32 v180, 16, v219
	v_and_b32_e32 v181, 0xffff0000, v219
	v_lshlrev_b32_e32 v244, 16, v227
	v_and_b32_e32 v245, 0xffff0000, v227
	v_rcp_f32_e32 v176, v176
	v_rcp_f32_e32 v177, v177
	v_rcp_f32_e32 v180, v180
	v_rcp_f32_e32 v181, v181
	s_nop 0
	v_pk_mul_f32 v[176:177], v[176:177], v[178:179]
	v_pk_mul_f32 v[180:181], v[180:181], v[244:245]
	v_pk_mul_f32 v[94:95], v[94:95], v[176:177]
	v_pk_mul_f32 v[96:97], v[96:97], v[180:181]
	v_lshlrev_b32_e32 v176, 16, v220
	v_and_b32_e32 v177, 0xffff0000, v220
	v_lshlrev_b32_e32 v178, 16, v228
	v_and_b32_e32 v179, 0xffff0000, v228
	v_lshlrev_b32_e32 v180, 16, v221
	v_and_b32_e32 v181, 0xffff0000, v221
	v_lshlrev_b32_e32 v244, 16, v229
	v_and_b32_e32 v245, 0xffff0000, v229
	v_rcp_f32_e32 v176, v176
	v_rcp_f32_e32 v177, v177
	v_rcp_f32_e32 v180, v180
	v_rcp_f32_e32 v181, v181
	s_nop 0
	v_pk_mul_f32 v[176:177], v[176:177], v[178:179]
	v_pk_mul_f32 v[180:181], v[180:181], v[244:245]
	v_pk_mul_f32 v[82:83], v[82:83], v[176:177]
	v_pk_mul_f32 v[84:85], v[84:85], v[180:181]
	v_lshlrev_b32_e32 v148, 16, v222
	v_and_b32_e32 v149, 0xffff0000, v222
	v_lshlrev_b32_e32 v150, 16, v230
	v_and_b32_e32 v151, 0xffff0000, v230
	v_lshlrev_b32_e32 v152, 16, v223
	v_and_b32_e32 v153, 0xffff0000, v223
	v_lshlrev_b32_e32 v168, 16, v231
	v_and_b32_e32 v169, 0xffff0000, v231
	v_rcp_f32_e32 v148, v148
	v_rcp_f32_e32 v149, v149
	v_rcp_f32_e32 v152, v152
	v_rcp_f32_e32 v153, v153
	s_nop 0
	v_pk_mul_f32 v[148:149], v[148:149], v[150:151]
	v_pk_mul_f32 v[152:153], v[152:153], v[168:169]
	v_pk_mul_f32 v[74:75], v[74:75], v[148:149]
	v_pk_mul_f32 v[76:77], v[76:77], v[152:153]
	s_add_u32 s100, s98, 0x1f4000
	s_addc_u32 s101, s99, 0
	global_load_dwordx4 v[216:219], v243, s[100:101]
	s_add_u32 s100, s98, 0x20d000
	s_addc_u32 s101, s99, 0
	global_load_dwordx4 v[220:223], v243, s[100:101]
	s_add_u32 s100, s98, 0x1f4000
	s_addc_u32 s101, s99, 0
	global_load_dwordx4 v[224:227], v243, s[100:101] offset:2048
	s_add_u32 s100, s98, 0x20d000
	s_addc_u32 s101, s99, 0
	global_load_dwordx4 v[228:231], v243, s[100:101] offset:2048
	s_waitcnt vmcnt(12)
; DI float bflo(unsigned w) { return __uint_as_float(w << 16); }
; DI float bfhi(unsigned w) { return __uint_as_float(w & 0xffff0000u); }
;     DI void operator()(Acc& acc, const Unit& u, int wr, int wc, int fr, int fq) const {
;     ...
;                     for (int bj = 0; bj < 2; ++bj) g[ai][m][bj] = *(const u32x4*)(base + (size_t)(ai * 128 + m * 16) * NPJ + u.k * 1024 + bj * 128);
; #pragma unroll
;             for (int ai = 0; ai < 2; ++ai)
; #pragma unroll
;                 for (int m = 0; m < 4; ++m)
; #pragma unroll
;                     for (int bj = 0; bj < 2; ++bj) { const u32x4 q = g[ai][m][bj]; f32x4& v0 = acc[ai][bj][m][0]; f32x4& v1 = acc[ai][bj][m][1];
;                         v0[0] *= bflo(q.x); v0[1] *= bfhi(q.x); v0[2] *= bflo(q.y); v0[3] *= bfhi(q.y); v1[0] *= bflo(q.z); v1[1] *= bfhi(q.z); v1[2] *= bflo(q.w); v1[3] *= bfhi(q.w); }
	v_lshlrev_b32_e32 v148, 16, v232
	v_and_b32_e32 v149, 0xffff0000, v232
	v_lshlrev_b32_e32 v150, 16, v132
	v_and_b32_e32 v151, 0xffff0000, v132
	v_lshlrev_b32_e32 v152, 16, v233
	v_and_b32_e32 v153, 0xffff0000, v233
	v_lshlrev_b32_e32 v168, 16, v133
	v_and_b32_e32 v169, 0xffff0000, v133
	v_rcp_f32_e32 v148, v148
	v_rcp_f32_e32 v149, v149
	v_rcp_f32_e32 v152, v152
	v_rcp_f32_e32 v153, v153
	s_nop 0
	v_pk_mul_f32 v[148:149], v[148:149], v[150:151]
	v_pk_mul_f32 v[152:153], v[152:153], v[168:169]
	v_pk_mul_f32 v[86:87], v[86:87], v[148:149]
	v_pk_mul_f32 v[88:89], v[88:89], v[152:153]
	v_lshlrev_b32_e32 v176, 16, v234
	v_and_b32_e32 v177, 0xffff0000, v234
	v_lshlrev_b32_e32 v178, 16, v134
	v_and_b32_e32 v179, 0xffff0000, v134
	v_lshlrev_b32_e32 v180, 16, v235
	v_and_b32_e32 v181, 0xffff0000, v235
	v_lshlrev_b32_e32 v244, 16, v135
	v_and_b32_e32 v245, 0xffff0000, v135
	v_rcp_f32_e32 v176, v176
	v_rcp_f32_e32 v177, v177
	v_rcp_f32_e32 v180, v180
	v_rcp_f32_e32 v181, v181
	s_nop 0
	v_pk_mul_f32 v[176:177], v[176:177], v[178:179]
	v_pk_mul_f32 v[180:181], v[180:181], v[244:245]
	v_pk_mul_f32 v[78:79], v[78:79], v[176:177]
	v_pk_mul_f32 v[80:81], v[80:81], v[180:181]
	v_lshlrev_b32_e32 v176, 16, v236
	v_and_b32_e32 v177, 0xffff0000, v236
	v_lshlrev_b32_e32 v178, 16, v136
	v_and_b32_e32 v179, 0xffff0000, v136
	v_lshlrev_b32_e32 v180, 16, v237
	v_and_b32_e32 v181, 0xffff0000, v237
	v_lshlrev_b32_e32 v244, 16, v137
	v_and_b32_e32 v245, 0xffff0000, v137
	v_rcp_f32_e32 v176, v176
	v_rcp_f32_e32 v177, v177
	v_rcp_f32_e32 v180, v180
	v_rcp_f32_e32 v181, v181
	s_nop 0
	v_pk_mul_f32 v[176:177], v[176:177], v[178:179]
	v_pk_mul_f32 v[180:181], v[180:181], v[244:245]
	v_pk_mul_f32 v[70:71], v[70:71], v[176:177]
	v_pk_mul_f32 v[72:73], v[72:73], v[180:181]
	v_lshlrev_b32_e32 v148, 16, v238
	v_and_b32_e32 v149, 0xffff0000, v238
	v_lshlrev_b32_e32 v150, 16, v138
	v_and_b32_e32 v151, 0xffff0000, v138
	v_lshlrev_b32_e32 v152, 16, v239
	v_and_b32_e32 v153, 0xffff0000, v239
	v_lshlrev_b32_e32 v168, 16, v139
	v_and_b32_e32 v169, 0xffff0000, v139
	v_rcp_f32_e32 v148, v148
	v_rcp_f32_e32 v149, v149
	v_rcp_f32_e32 v152, v152
	v_rcp_f32_e32 v153, v153
	s_nop 0
	v_pk_mul_f32 v[148:149], v[148:149], v[150:151]
	v_pk_mul_f32 v[152:153], v[152:153], v[168:169]
	v_pk_mul_f32 v[66:67], v[66:67], v[148:149]
	v_pk_mul_f32 v[68:69], v[68:69], v[152:153]
	s_add_u32 s100, s98, 0x226000
	s_addc_u32 s101, s99, 0
	global_load_dwordx4 v[232:235], v243, s[100:101]
	s_add_u32 s100, s98, 0x23f000
	s_addc_u32 s101, s99, 0
	global_load_dwordx4 v[236:239], v243, s[100:101]
	s_add_u32 s100, s98, 0x226000
	s_addc_u32 s101, s99, 0
	global_load_dwordx4 v[132:135], v243, s[100:101] offset:2048
	s_add_u32 s100, s98, 0x23f000
	s_addc_u32 s101, s99, 0
	global_load_dwordx4 v[136:139], v243, s[100:101] offset:2048
	s_waitcnt vmcnt(12)
	v_lshlrev_b32_e32 v148, 16, v184
	v_and_b32_e32 v149, 0xffff0000, v184
	v_lshlrev_b32_e32 v150, 16, v192
	v_and_b32_e32 v151, 0xffff0000, v192
	v_lshlrev_b32_e32 v152, 16, v185
	v_and_b32_e32 v153, 0xffff0000, v185
	v_lshlrev_b32_e32 v168, 16, v193
	v_and_b32_e32 v169, 0xffff0000, v193
	v_rcp_f32_e32 v148, v148
	v_rcp_f32_e32 v149, v149
	v_rcp_f32_e32 v152, v152
	v_rcp_f32_e32 v153, v153
	s_nop 0
	v_pk_mul_f32 v[148:149], v[148:149], v[150:151]
	v_pk_mul_f32 v[152:153], v[152:153], v[168:169]
	v_pk_mul_f32 v[62:63], v[62:63], v[148:149]
	v_pk_mul_f32 v[64:65], v[64:65], v[152:153]
	v_lshlrev_b32_e32 v176, 16, v186
	v_and_b32_e32 v177, 0xffff0000, v186
	v_lshlrev_b32_e32 v178, 16, v194
	v_and_b32_e32 v179, 0xffff0000, v194
	v_lshlrev_b32_e32 v180, 16, v187
	v_and_b32_e32 v181, 0xffff0000, v187
	v_lshlrev_b32_e32 v244, 16, v195
	v_and_b32_e32 v245, 0xffff0000, v195
	v_rcp_f32_e32 v176, v176
	v_rcp_f32_e32 v177, v177
	v_rcp_f32_e32 v180, v180
	v_rcp_f32_e32 v181, v181
	s_nop 0
	v_pk_mul_f32 v[176:177], v[176:177], v[178:179]
	v_pk_mul_f32 v[180:181], v[180:181], v[244:245]
	v_pk_mul_f32 v[58:59], v[58:59], v[176:177]
	v_pk_mul_f32 v[60:61], v[60:61], v[180:181]
	v_lshlrev_b32_e32 v176, 16, v188
	v_and_b32_e32 v177, 0xffff0000, v188
	v_lshlrev_b32_e32 v178, 16, v196
	v_and_b32_e32 v179, 0xffff0000, v196
	v_lshlrev_b32_e32 v180, 16, v189
	v_and_b32_e32 v181, 0xffff0000, v189
	v_lshlrev_b32_e32 v244, 16, v197
	v_and_b32_e32 v245, 0xffff0000, v197
	v_rcp_f32_e32 v176, v176
	v_rcp_f32_e32 v177, v177
	v_rcp_f32_e32 v180, v180
	v_rcp_f32_e32 v181, v181
	s_nop 0
	v_pk_mul_f32 v[176:177], v[176:177], v[178:179]
	v_pk_mul_f32 v[180:181], v[180:181], v[244:245]
	v_pk_mul_f32 v[50:51], v[50:51], v[176:177]
	v_pk_mul_f32 v[52:53], v[52:53], v[180:181]
	v_lshlrev_b32_e32 v148, 16, v190
	v_and_b32_e32 v149, 0xffff0000, v190
	v_lshlrev_b32_e32 v150, 16, v198
	v_and_b32_e32 v151, 0xffff0000, v198
	v_lshlrev_b32_e32 v152, 16, v191
	v_and_b32_e32 v153, 0xffff0000, v191
	v_lshlrev_b32_e32 v168, 16, v199
	v_and_b32_e32 v169, 0xffff0000, v199
	v_rcp_f32_e32 v148, v148
	v_rcp_f32_e32 v149, v149
	v_rcp_f32_e32 v152, v152
	v_rcp_f32_e32 v153, v153
	s_nop 0
	v_pk_mul_f32 v[148:149], v[148:149], v[150:151]
	v_pk_mul_f32 v[152:153], v[152:153], v[168:169]
	v_pk_mul_f32 v[42:43], v[42:43], v[148:149]
	v_pk_mul_f32 v[44:45], v[44:45], v[152:153]
	s_waitcnt vmcnt(8)
; DI float bflo(unsigned w) { return __uint_as_float(w << 16); }
; DI float bfhi(unsigned w) { return __uint_as_float(w & 0xffff0000u); }
;     DI void operator()(Acc& acc, const Unit& u, int wr, int wc, int fr, int fq) const {
;     ...
;                     for (int bj = 0; bj < 2; ++bj) g[ai][m][bj] = *(const u32x4*)(base + (size_t)(ai * 128 + m * 16) * NPJ + u.k * 1024 + bj * 128);
; #pragma unroll
;             for (int ai = 0; ai < 2; ++ai)
; #pragma unroll
;                 for (int m = 0; m < 4; ++m)
; #pragma unroll
;                     for (int bj = 0; bj < 2; ++bj) { const u32x4 q = g[ai][m][bj]; f32x4& v0 = acc[ai][bj][m][0]; f32x4& v1 = acc[ai][bj][m][1];
;                         v0[0] *= bflo(q.x); v0[1] *= bfhi(q.x); v0[2] *= bflo(q.y); v0[3] *= bfhi(q.y); v1[0] *= bflo(q.z); v1[1] *= bfhi(q.z); v1[2] *= bflo(q.w); v1[3] *= bfhi(q.w); }
	v_lshlrev_b32_e32 v148, 16, v200
	v_and_b32_e32 v149, 0xffff0000, v200
	v_lshlrev_b32_e32 v150, 16, v208
	v_and_b32_e32 v151, 0xffff0000, v208
	v_lshlrev_b32_e32 v152, 16, v201
	v_and_b32_e32 v153, 0xffff0000, v201
	v_lshlrev_b32_e32 v168, 16, v209
	v_and_b32_e32 v169, 0xffff0000, v209
	v_rcp_f32_e32 v148, v148
	v_rcp_f32_e32 v149, v149
	v_rcp_f32_e32 v152, v152
	v_rcp_f32_e32 v153, v153
	s_nop 0
	v_pk_mul_f32 v[148:149], v[148:149], v[150:151]
	v_pk_mul_f32 v[152:153], v[152:153], v[168:169]
	v_pk_mul_f32 v[54:55], v[54:55], v[148:149]
	v_pk_mul_f32 v[56:57], v[56:57], v[152:153]
	v_lshlrev_b32_e32 v176, 16, v202
	v_and_b32_e32 v177, 0xffff0000, v202
	v_lshlrev_b32_e32 v178, 16, v210
	v_and_b32_e32 v179, 0xffff0000, v210
	v_lshlrev_b32_e32 v180, 16, v203
	v_and_b32_e32 v181, 0xffff0000, v203
	v_lshlrev_b32_e32 v244, 16, v211
	v_and_b32_e32 v245, 0xffff0000, v211
	v_rcp_f32_e32 v176, v176
	v_rcp_f32_e32 v177, v177
	v_rcp_f32_e32 v180, v180
	v_rcp_f32_e32 v181, v181
	s_nop 0
	v_pk_mul_f32 v[176:177], v[176:177], v[178:179]
	v_pk_mul_f32 v[180:181], v[180:181], v[244:245]
	v_pk_mul_f32 v[46:47], v[46:47], v[176:177]
	v_pk_mul_f32 v[48:49], v[48:49], v[180:181]
	v_lshlrev_b32_e32 v176, 16, v204
	v_and_b32_e32 v177, 0xffff0000, v204
	v_lshlrev_b32_e32 v178, 16, v212
	v_and_b32_e32 v179, 0xffff0000, v212
	v_lshlrev_b32_e32 v180, 16, v205
	v_and_b32_e32 v181, 0xffff0000, v205
	v_lshlrev_b32_e32 v244, 16, v213
	v_and_b32_e32 v245, 0xffff0000, v213
	v_rcp_f32_e32 v176, v176
	v_rcp_f32_e32 v177, v177
	v_rcp_f32_e32 v180, v180
	v_rcp_f32_e32 v181, v181
	s_nop 0
	v_pk_mul_f32 v[176:177], v[176:177], v[178:179]
	v_pk_mul_f32 v[180:181], v[180:181], v[244:245]
	v_pk_mul_f32 v[34:35], v[34:35], v[176:177]
	v_pk_mul_f32 v[36:37], v[36:37], v[180:181]
	v_lshlrev_b32_e32 v148, 16, v206
	v_and_b32_e32 v149, 0xffff0000, v206
	v_lshlrev_b32_e32 v150, 16, v214
	v_and_b32_e32 v151, 0xffff0000, v214
	v_lshlrev_b32_e32 v152, 16, v207
	v_and_b32_e32 v153, 0xffff0000, v207
	v_lshlrev_b32_e32 v168, 16, v215
	v_and_b32_e32 v169, 0xffff0000, v215
	v_rcp_f32_e32 v148, v148
	v_rcp_f32_e32 v149, v149
	v_rcp_f32_e32 v152, v152
	v_rcp_f32_e32 v153, v153
	s_nop 0
	v_pk_mul_f32 v[148:149], v[148:149], v[150:151]
	v_pk_mul_f32 v[152:153], v[152:153], v[168:169]
	v_pk_mul_f32 v[26:27], v[26:27], v[148:149]
	v_pk_mul_f32 v[28:29], v[28:29], v[152:153]
	s_waitcnt vmcnt(4)
; DI float bflo(unsigned w) { return __uint_as_float(w << 16); }
; DI float bfhi(unsigned w) { return __uint_as_float(w & 0xffff0000u); }
;     DI void operator()(Acc& acc, const Unit& u, int wr, int wc, int fr, int fq) const {
;     ...
;                     for (int bj = 0; bj < 2; ++bj) g[ai][m][bj] = *(const u32x4*)(base + (size_t)(ai * 128 + m * 16) * NPJ + u.k * 1024 + bj * 128);
; #pragma unroll
;             for (int ai = 0; ai < 2; ++ai)
; #pragma unroll
;                 for (int m = 0; m < 4; ++m)
; #pragma unroll
;                     for (int bj = 0; bj < 2; ++bj) { const u32x4 q = g[ai][m][bj]; f32x4& v0 = acc[ai][bj][m][0]; f32x4& v1 = acc[ai][bj][m][1];
;                         v0[0] *= bflo(q.x); v0[1] *= bfhi(q.x); v0[2] *= bflo(q.y); v0[3] *= bfhi(q.y); v1[0] *= bflo(q.z); v1[1] *= bfhi(q.z); v1[2] *= bflo(q.w); v1[3] *= bfhi(q.w); }
	v_lshlrev_b32_e32 v148, 16, v216
	v_and_b32_e32 v149, 0xffff0000, v216
	v_lshlrev_b32_e32 v150, 16, v224
	v_and_b32_e32 v151, 0xffff0000, v224
	v_lshlrev_b32_e32 v152, 16, v217
	v_and_b32_e32 v153, 0xffff0000, v217
	v_lshlrev_b32_e32 v168, 16, v225
	v_and_b32_e32 v169, 0xffff0000, v225
	v_rcp_f32_e32 v148, v148
	v_rcp_f32_e32 v149, v149
	v_rcp_f32_e32 v152, v152
	v_rcp_f32_e32 v153, v153
	s_nop 0
	v_pk_mul_f32 v[148:149], v[148:149], v[150:151]
	v_pk_mul_f32 v[152:153], v[152:153], v[168:169]
	v_pk_mul_f32 v[38:39], v[38:39], v[148:149]
	v_pk_mul_f32 v[40:41], v[40:41], v[152:153]
	v_lshlrev_b32_e32 v176, 16, v218
	v_and_b32_e32 v177, 0xffff0000, v218
	v_lshlrev_b32_e32 v178, 16, v226
	v_and_b32_e32 v179, 0xffff0000, v226
	v_lshlrev_b32_e32 v180, 16, v219
	v_and_b32_e32 v181, 0xffff0000, v219
	v_lshlrev_b32_e32 v244, 16, v227
	v_and_b32_e32 v245, 0xffff0000, v227
	v_rcp_f32_e32 v176, v176
	v_rcp_f32_e32 v177, v177
	v_rcp_f32_e32 v180, v180
	v_rcp_f32_e32 v181, v181
	s_nop 0
	v_pk_mul_f32 v[176:177], v[176:177], v[178:179]
	v_pk_mul_f32 v[180:181], v[180:181], v[244:245]
	v_pk_mul_f32 v[30:31], v[30:31], v[176:177]
	v_pk_mul_f32 v[32:33], v[32:33], v[180:181]
	v_lshlrev_b32_e32 v176, 16, v220
	v_and_b32_e32 v177, 0xffff0000, v220
	v_lshlrev_b32_e32 v178, 16, v228
	v_and_b32_e32 v179, 0xffff0000, v228
	v_lshlrev_b32_e32 v180, 16, v221
	v_and_b32_e32 v181, 0xffff0000, v221
	v_lshlrev_b32_e32 v244, 16, v229
	v_and_b32_e32 v245, 0xffff0000, v229
	v_rcp_f32_e32 v176, v176
	v_rcp_f32_e32 v177, v177
	v_rcp_f32_e32 v180, v180
	v_rcp_f32_e32 v181, v181
	s_nop 0
	v_pk_mul_f32 v[176:177], v[176:177], v[178:179]
	v_pk_mul_f32 v[180:181], v[180:181], v[244:245]
	v_pk_mul_f32 v[18:19], v[18:19], v[176:177]
	v_pk_mul_f32 v[20:21], v[20:21], v[180:181]
	v_lshlrev_b32_e32 v148, 16, v222
	v_and_b32_e32 v149, 0xffff0000, v222
	v_lshlrev_b32_e32 v150, 16, v230
	v_and_b32_e32 v151, 0xffff0000, v230
	v_lshlrev_b32_e32 v152, 16, v223
	v_and_b32_e32 v153, 0xffff0000, v223
	v_lshlrev_b32_e32 v168, 16, v231
	v_and_b32_e32 v169, 0xffff0000, v231
	v_rcp_f32_e32 v148, v148
	v_rcp_f32_e32 v149, v149
	v_rcp_f32_e32 v152, v152
	v_rcp_f32_e32 v153, v153
	s_nop 0
	v_pk_mul_f32 v[148:149], v[148:149], v[150:151]
	v_pk_mul_f32 v[152:153], v[152:153], v[168:169]
	v_pk_mul_f32 v[10:11], v[10:11], v[148:149]
	v_pk_mul_f32 v[12:13], v[12:13], v[152:153]
	s_waitcnt vmcnt(0)
	v_lshlrev_b32_e32 v148, 16, v232
	v_and_b32_e32 v149, 0xffff0000, v232
	v_lshlrev_b32_e32 v150, 16, v132
	v_and_b32_e32 v151, 0xffff0000, v132
	v_lshlrev_b32_e32 v152, 16, v233
	v_and_b32_e32 v153, 0xffff0000, v233
	v_lshlrev_b32_e32 v168, 16, v133
	v_and_b32_e32 v169, 0xffff0000, v133
	v_rcp_f32_e32 v148, v148
	v_rcp_f32_e32 v149, v149
	v_rcp_f32_e32 v152, v152
	v_rcp_f32_e32 v153, v153
	s_nop 0
	v_pk_mul_f32 v[148:149], v[148:149], v[150:151]
	v_pk_mul_f32 v[152:153], v[152:153], v[168:169]
	v_pk_mul_f32 v[22:23], v[22:23], v[148:149]
	v_pk_mul_f32 v[24:25], v[24:25], v[152:153]
	v_lshlrev_b32_e32 v176, 16, v234
	v_and_b32_e32 v177, 0xffff0000, v234
	v_lshlrev_b32_e32 v178, 16, v134
	v_and_b32_e32 v179, 0xffff0000, v134
	v_lshlrev_b32_e32 v180, 16, v235
	v_and_b32_e32 v181, 0xffff0000, v235
	v_lshlrev_b32_e32 v244, 16, v135
	v_and_b32_e32 v245, 0xffff0000, v135
	v_rcp_f32_e32 v176, v176
	v_rcp_f32_e32 v177, v177
	v_rcp_f32_e32 v180, v180
	v_rcp_f32_e32 v181, v181
	s_nop 0
	v_pk_mul_f32 v[176:177], v[176:177], v[178:179]
	v_pk_mul_f32 v[180:181], v[180:181], v[244:245]
	v_pk_mul_f32 v[14:15], v[14:15], v[176:177]
	v_pk_mul_f32 v[16:17], v[16:17], v[180:181]
	v_lshlrev_b32_e32 v176, 16, v236
	v_and_b32_e32 v177, 0xffff0000, v236
	v_lshlrev_b32_e32 v178, 16, v136
	v_and_b32_e32 v179, 0xffff0000, v136
	v_lshlrev_b32_e32 v180, 16, v237
	v_and_b32_e32 v181, 0xffff0000, v237
	v_lshlrev_b32_e32 v244, 16, v137
	v_and_b32_e32 v245, 0xffff0000, v137
	v_rcp_f32_e32 v176, v176
	v_rcp_f32_e32 v177, v177
	v_rcp_f32_e32 v180, v180
	v_rcp_f32_e32 v181, v181
	s_nop 0
	v_pk_mul_f32 v[176:177], v[176:177], v[178:179]
	v_pk_mul_f32 v[180:181], v[180:181], v[244:245]
	v_pk_mul_f32 v[6:7], v[6:7], v[176:177]
	v_pk_mul_f32 v[8:9], v[8:9], v[180:181]
	v_lshlrev_b32_e32 v148, 16, v238
	v_and_b32_e32 v149, 0xffff0000, v238
	v_lshlrev_b32_e32 v150, 16, v138
	v_and_b32_e32 v151, 0xffff0000, v138
	v_lshlrev_b32_e32 v152, 16, v239
	v_and_b32_e32 v153, 0xffff0000, v239
	v_lshlrev_b32_e32 v168, 16, v139
	v_and_b32_e32 v169, 0xffff0000, v139
	v_rcp_f32_e32 v148, v148
	v_rcp_f32_e32 v149, v149
	v_rcp_f32_e32 v152, v152
	v_rcp_f32_e32 v153, v153
	s_nop 0
	v_pk_mul_f32 v[148:149], v[148:149], v[150:151]
	v_pk_mul_f32 v[152:153], v[152:153], v[168:169]
	v_pk_mul_f32 v[2:3], v[2:3], v[148:149]
	v_pk_mul_f32 v[4:5], v[4:5], v[152:153]
	s_branch .Lup6_tail
